# same as previous best plus a grid-size guard: phase-0 work relocation into idle GEMM-tail workgroups only when the grid has 256 workgroups
# baseline (speedup 1.0000x reference)
.LBB0_78:
	v_readlane_b32 s80, v255, 42
	v_readlane_b32 s84, v255, 44
	v_readlane_b32 s81, v255, 43
	v_readlane_b32 s85, v255, 45
	v_readlane_b32 s77, v255, 46
	v_readlane_b32 s76, v255, 47
	s_barrier
	s_cmpk_lg_u32 s54, 0x100
	s_cbranch_scc1 .Lp0t_end_q10
	v_readlane_b32 s0, v255, 48
	s_cmp_eq_u32 s0, 11
	s_cbranch_scc0 .Lp0t_n0_q10
	s_cmp_lt_u32 s34, 64
	s_cbranch_scc1 .Lp0t_n0_q10
	s_sub_i32 s45, s34, 64
	s_add_i32 s45, s45, 0x120
	s_mov_b32 s68, 0xc0
	s_mov_b32 s69, 0x39f
	s_mov_b32 s58, 0x240
	s_mov_b32 s59, 0x420
	s_mov_b32 s61, 0x7fffffff
	s_mov_b32 s74, 0x0
	s_mov_b32 s78, 0x7fffffff
	s_mov_b32 s79, 0x0
	s_mov_b32 s70, 0x0
	s_mov_b32 s71, 0x0
	s_cmp_gt_i32 s45, s69
	s_cbranch_scc1 .Lp0t_n0_q10
	s_branch .Lp0_tramp

.LBB0_430:
	v_readlane_b32 s84, v255, 44
	v_readlane_b32 s85, v255, 45
	v_readlane_b32 s77, v255, 46
	v_readlane_b32 s76, v255, 47
	s_barrier
	s_cmpk_lg_u32 s54, 0x100
	s_cbranch_scc1 .Lp0t_end_q4a
	v_readlane_b32 s0, v255, 48
	s_cmp_eq_u32 s0, 5
	s_cbranch_scc0 .Lp0t_n0_q4a
	s_cmp_lt_u32 s34, 192
	s_cbranch_scc1 .Lp0t_n0_q4a
	s_sub_i32 s45, s34, 192
	s_add_i32 s45, s45, 0xb20
	s_mov_b32 s68, 0x40
	s_mov_b32 s69, 0xbff
	s_mov_b32 s58, 0x7fffffff
	s_mov_b32 s59, 0x0
	s_mov_b32 s61, 0x7fffffff
	s_mov_b32 s74, 0x0
	s_mov_b32 s78, 0x7fffffff
	s_mov_b32 s79, 0x0
	s_mov_b32 s70, 0x0
	s_mov_b32 s71, 0x0
	s_cmp_gt_i32 s45, s69
	s_cbranch_scc1 .Lp0t_n0_q4a
	s_branch .Lp0_full

.LBB0_451:
	s_barrier
	s_cmpk_lg_u32 s54, 0x100
	s_cbranch_scc1 .Lp0t_end_q4b
	v_readlane_b32 s0, v255, 48
	s_cmp_eq_u32 s0, 5
	s_cbranch_scc0 .Lp0t_n0_q4b
	s_cmp_lt_u32 s34, 192
	s_cbranch_scc1 .Lp0t_n0_q4b
	s_sub_i32 s45, s34, 192
	s_add_i32 s45, s45, 0xb20
	s_mov_b32 s68, 0x40
	s_mov_b32 s69, 0xbff
	s_mov_b32 s58, 0x7fffffff
	s_mov_b32 s59, 0x0
	s_mov_b32 s61, 0x7fffffff
	s_mov_b32 s74, 0x0
	s_mov_b32 s78, 0x7fffffff
	s_mov_b32 s79, 0x0
	s_mov_b32 s70, 0x0
	s_mov_b32 s71, 0x0
	s_cmp_gt_i32 s45, s69
	s_cbranch_scc1 .Lp0t_n0_q4b
	s_branch .Lp0_full

.LBB0_527:
	v_readlane_b32 s80, v255, 42
	v_readlane_b32 s84, v255, 44
	v_readlane_b32 s81, v255, 43
	v_readlane_b32 s85, v255, 45
	v_readlane_b32 s77, v255, 46
	v_readlane_b32 s76, v255, 47
	s_barrier
	s_cmpk_lg_u32 s54, 0x100
	s_cbranch_scc1 .Lp0t_end_q1
	v_readlane_b32 s0, v255, 48
	s_cmp_eq_u32 s0, 2
	s_cbranch_scc0 .Lp0t_n0_q1
	s_cmp_lt_u32 s34, 64
	s_cbranch_scc1 .Lp0t_n0_q1
	s_sub_i32 s45, s34, 64
	s_add_i32 s45, s45, 0x450
	s_mov_b32 s68, 0xc0
	s_mov_b32 s69, 0x95f
	s_mov_b32 s58, 0x660
	s_mov_b32 s59, 0x660
	s_mov_b32 s61, 0x860
	s_mov_b32 s74, 0x100
	s_mov_b32 s78, 0x7fffffff
	s_mov_b32 s79, 0x0
	s_mov_b32 s70, 0x0
	s_mov_b32 s71, 0x0
	s_cmp_gt_i32 s45, s69
	s_cbranch_scc1 .Lp0t_n0_q1
	s_branch .Lp0_full

.LBB0_556:
	s_and_b64 vcc, exec, s[0:1]
	s_cbranch_vccz .LBB0_622
	s_mov_b32 s45, s34
	s_mov_b32 s68, s54
	s_mov_b32 s69, 0x44f
	s_mov_b32 s58, 0x120
	s_mov_b32 s59, 0x120
	s_mov_b32 s61, 0x330
	s_mov_b32 s74, 0x630
	s_mov_b32 s78, 0x3d0
	s_mov_b32 s79, 0xe0
	s_mov_b32 s70, 0x0
	s_mov_b32 s71, 0x0
	s_cmpk_eq_u32 s54, 0x100
	s_cbranch_scc1 .Lp0_full
	s_mov_b32 s45, s34
	s_mov_b32 s68, s54
	s_mov_b32 s69, 0x10bf
	s_mov_b32 s58, 0x7fffffff
	s_mov_b32 s59, 0x0
	s_mov_b32 s61, 0x7fffffff
	s_mov_b32 s74, 0x0
	s_mov_b32 s78, 0x7fffffff
	s_mov_b32 s79, 0x0
	s_mov_b32 s70, 0x0
	s_mov_b32 s71, 0x0
